# GEMM K-loop: compiler vmcnt(0) at loop head hoisted to preheader
# baseline (speedup 1.0000x reference)
.LBB0_597:
	s_add_u32 s80, s4, 0x80
	s_addc_u32 s81, s5, 0
	s_add_u32 s4, s0, 0x100
	v_mov_b32_e32 v60, 0
	s_addc_u32 s5, s1, 0
	s_mov_b32 s0, 0
	v_mov_b32_e32 v61, v60
	v_mov_b32_e32 v62, v60
	v_mov_b32_e32 v63, v60
	v_mov_b32_e32 v64, v60
	v_mov_b32_e32 v65, v60
	v_mov_b32_e32 v66, v60
	v_mov_b32_e32 v67, v60
	v_mov_b32_e32 v72, v60
	v_mov_b32_e32 v73, v60
	v_mov_b32_e32 v74, v60
	v_mov_b32_e32 v75, v60
	v_mov_b32_e32 v76, v60
	v_mov_b32_e32 v77, v60
	v_mov_b32_e32 v78, v60
	v_mov_b32_e32 v79, v60
	v_mov_b32_e32 v80, v60
	v_mov_b32_e32 v81, v60
	v_mov_b32_e32 v82, v60
	v_mov_b32_e32 v83, v60
	v_mov_b32_e32 v84, v60
	v_mov_b32_e32 v85, v60
	v_mov_b32_e32 v86, v60
	v_mov_b32_e32 v87, v60
	v_mov_b32_e32 v88, v60
	v_mov_b32_e32 v89, v60
	v_mov_b32_e32 v90, v60
	v_mov_b32_e32 v91, v60
	v_mov_b32_e32 v92, v60
	v_mov_b32_e32 v93, v60
	v_mov_b32_e32 v94, v60
	v_mov_b32_e32 v95, v60
	v_mov_b32_e32 v0, v60
	v_mov_b32_e32 v1, v60
	v_mov_b32_e32 v2, v60
	v_mov_b32_e32 v3, v60
	v_mov_b32_e32 v4, v60
	v_mov_b32_e32 v5, v60
	v_mov_b32_e32 v6, v60
	v_mov_b32_e32 v7, v60
	v_mov_b32_e32 v8, v60
	v_mov_b32_e32 v9, v60
	v_mov_b32_e32 v10, v60
	v_mov_b32_e32 v11, v60
	v_mov_b32_e32 v12, v60
	v_mov_b32_e32 v13, v60
	v_mov_b32_e32 v14, v60
	v_mov_b32_e32 v15, v60
	v_mov_b32_e32 v16, v60
	v_mov_b32_e32 v17, v60
	v_mov_b32_e32 v18, v60
	v_mov_b32_e32 v19, v60
	v_mov_b32_e32 v20, v60
	v_mov_b32_e32 v21, v60
	v_mov_b32_e32 v22, v60
	v_mov_b32_e32 v23, v60
	v_mov_b32_e32 v24, v60
	v_mov_b32_e32 v25, v60
	v_mov_b32_e32 v26, v60
	v_mov_b32_e32 v27, v60
	v_mov_b32_e32 v28, v60
	v_mov_b32_e32 v29, v60
	v_mov_b32_e32 v30, v60
	v_mov_b32_e32 v31, v60
	v_mov_b32_e32 v96, v60
	v_mov_b32_e32 v97, v60
	v_mov_b32_e32 v98, v60
	v_mov_b32_e32 v99, v60
	v_mov_b32_e32 v100, v60
	v_mov_b32_e32 v101, v60
	v_mov_b32_e32 v102, v60
	v_mov_b32_e32 v103, v60
	v_mov_b32_e32 v104, v60
	v_mov_b32_e32 v105, v60
	v_mov_b32_e32 v106, v60
	v_mov_b32_e32 v107, v60
	v_mov_b32_e32 v108, v60
	v_mov_b32_e32 v109, v60
	v_mov_b32_e32 v110, v60
	v_mov_b32_e32 v111, v60
	v_mov_b32_e32 v114, v60
	v_mov_b32_e32 v115, v60
	v_mov_b32_e32 v116, v60
	v_mov_b32_e32 v117, v60
	v_mov_b32_e32 v118, v60
	v_mov_b32_e32 v119, v60
	v_mov_b32_e32 v120, v60
	v_mov_b32_e32 v121, v60
	v_mov_b32_e32 v122, v60
	v_mov_b32_e32 v123, v60
	v_mov_b32_e32 v124, v60
	v_mov_b32_e32 v125, v60
	v_mov_b32_e32 v126, v60
	v_mov_b32_e32 v127, v60
	v_mov_b32_e32 v128, v60
	v_mov_b32_e32 v129, v60
	v_mov_b32_e32 v32, v60
	v_mov_b32_e32 v33, v60
	v_mov_b32_e32 v34, v60
	v_mov_b32_e32 v35, v60
	v_mov_b32_e32 v36, v60
	v_mov_b32_e32 v37, v60
	v_mov_b32_e32 v38, v60
	v_mov_b32_e32 v39, v60
	v_mov_b32_e32 v40, v60
	v_mov_b32_e32 v41, v60
	v_mov_b32_e32 v42, v60
	v_mov_b32_e32 v43, v60
	v_mov_b32_e32 v44, v60
	v_mov_b32_e32 v45, v60
	v_mov_b32_e32 v46, v60
	v_mov_b32_e32 v47, v60
	v_mov_b32_e32 v48, v60
	v_mov_b32_e32 v49, v60
	v_mov_b32_e32 v50, v60
	v_mov_b32_e32 v51, v60
	v_mov_b32_e32 v52, v60
	v_mov_b32_e32 v53, v60
	v_mov_b32_e32 v54, v60
	v_mov_b32_e32 v55, v60
	v_mov_b32_e32 v56, v60
	v_mov_b32_e32 v57, v60
	v_mov_b32_e32 v58, v60
	v_mov_b32_e32 v59, v60
	v_mov_b32_e32 v68, v60
	v_mov_b32_e32 v69, v60
	v_mov_b32_e32 v70, v60
	v_mov_b32_e32 v71, v60
	s_waitcnt vmcnt(0)
.LBB0_598:
	v_add_u32_e32 v142, s31, v201
	v_add_u32_e32 v158, s56, v201
	ds_read_b128 v[130:133], v142
	ds_read_b128 v[134:137], v142 offset:1024
	ds_read_b128 v[138:141], v142 offset:2048
	ds_read_b128 v[142:145], v142 offset:3072
	ds_read_b128 v[146:149], v158
	ds_read_b128 v[150:153], v158 offset:1024
	ds_read_b128 v[154:157], v158 offset:2048
	ds_read_b128 v[158:161], v158 offset:3072
	s_add_i32 s6, s0, 2
	s_add_u32 s7, s80, 0x80
	s_addc_u32 s1, s81, 0
	s_cmp_eq_u32 s95, s0
	s_cselect_b32 s0, s46, s7
	s_cselect_b32 s1, s47, s1
	s_cselect_b32 vcc_hi, s79, s5
	s_cselect_b32 vcc_lo, s78, s4
	v_lshl_add_u64 v[210:211], s[80:81], 0, v[168:169]
	s_add_i32 m0, s59, 0xc000
	ds_read_b128 v[172:175], v204
	ds_read_b128 v[176:179], v204 offset:1024
	ds_read_b128 v[180:183], v204 offset:2048
	ds_read_b128 v[184:187], v204 offset:3072
	ds_read_b128 v[188:191], v204 offset:4096
	ds_read_b128 v[192:195], v204 offset:5120
	ds_read_b128 v[196:199], v204 offset:6144
	ds_read_b128 v[206:209], v204 offset:7168
	global_load_lds_dwordx4 v[210:211], off
	v_lshl_add_u64 v[210:211], s[80:81], 0, v[170:171]
	s_add_i32 m0, s59, 0xe000
	s_nop 0
	global_load_lds_dwordx4 v[210:211], off
	s_waitcnt vmcnt(8)
	s_waitcnt lgkmcnt(0)
	s_barrier
	s_setprio 1
	s_waitcnt lgkmcnt(0)
	v_mfma_f32_16x16x32_bf16 v[68:71], v[130:133], v[172:175], v[68:71]
	v_mfma_f32_16x16x32_bf16 v[56:59], v[138:141], v[172:175], v[56:59]
	v_mfma_f32_16x16x32_bf16 v[52:55], v[130:133], v[180:183], v[52:55]
	v_mfma_f32_16x16x32_bf16 v[48:51], v[138:141], v[180:183], v[48:51]
	v_mfma_f32_16x16x32_bf16 v[44:47], v[130:133], v[188:191], v[44:47]
	v_mfma_f32_16x16x32_bf16 v[40:43], v[138:141], v[188:191], v[40:43]
	v_mfma_f32_16x16x32_bf16 v[36:39], v[130:133], v[196:199], v[36:39]
	v_mfma_f32_16x16x32_bf16 v[32:35], v[138:141], v[196:199], v[32:35]
	v_mfma_f32_16x16x32_bf16 v[68:71], v[134:137], v[176:179], v[68:71]
	v_mfma_f32_16x16x32_bf16 v[56:59], v[142:145], v[176:179], v[56:59]
	v_mfma_f32_16x16x32_bf16 v[52:55], v[134:137], v[184:187], v[52:55]
	v_mfma_f32_16x16x32_bf16 v[48:51], v[142:145], v[184:187], v[48:51]
	v_mfma_f32_16x16x32_bf16 v[44:47], v[134:137], v[192:195], v[44:47]
	v_mfma_f32_16x16x32_bf16 v[40:43], v[142:145], v[192:195], v[40:43]
	v_mfma_f32_16x16x32_bf16 v[36:39], v[134:137], v[206:209], v[36:39]
	v_mfma_f32_16x16x32_bf16 v[32:35], v[142:145], v[206:209], v[32:35]
	s_setprio 0
	s_setprio 1
	v_mfma_f32_16x16x32_bf16 v[126:129], v[146:149], v[172:175], v[126:129]
	v_mfma_f32_16x16x32_bf16 v[122:125], v[154:157], v[172:175], v[122:125]
	v_mfma_f32_16x16x32_bf16 v[118:121], v[146:149], v[180:183], v[118:121]
	v_mfma_f32_16x16x32_bf16 v[114:117], v[154:157], v[180:183], v[114:117]
	v_mfma_f32_16x16x32_bf16 v[108:111], v[146:149], v[188:191], v[108:111]
	v_mfma_f32_16x16x32_bf16 v[104:107], v[154:157], v[188:191], v[104:107]
	v_mfma_f32_16x16x32_bf16 v[100:103], v[146:149], v[196:199], v[100:103]
	v_mfma_f32_16x16x32_bf16 v[96:99], v[154:157], v[196:199], v[96:99]
	v_mfma_f32_16x16x32_bf16 v[126:129], v[150:153], v[176:179], v[126:129]
	v_mfma_f32_16x16x32_bf16 v[122:125], v[158:161], v[176:179], v[122:125]
	v_mfma_f32_16x16x32_bf16 v[118:121], v[150:153], v[184:187], v[118:121]
	v_mfma_f32_16x16x32_bf16 v[114:117], v[158:161], v[184:187], v[114:117]
	v_mfma_f32_16x16x32_bf16 v[108:111], v[150:153], v[192:195], v[108:111]
	v_mfma_f32_16x16x32_bf16 v[104:107], v[158:161], v[192:195], v[104:107]
	v_mfma_f32_16x16x32_bf16 v[100:103], v[150:153], v[206:209], v[100:103]
	v_mfma_f32_16x16x32_bf16 v[96:99], v[158:161], v[206:209], v[96:99]
	s_setprio 0
	s_barrier
	s_mov_b32 m0, s36
	v_lshl_add_u64 v[210:211], vcc, 0, v[112:113]
	v_lshl_add_u64 v[212:213], vcc, 0, v[166:167]
	s_add_u32 vcc_lo, vcc_lo, s66
	ds_read_b128 v[172:175], v204 offset:16384
	ds_read_b128 v[176:179], v204 offset:17408
	ds_read_b128 v[180:183], v204 offset:18432
	ds_read_b128 v[184:187], v204 offset:19456
	ds_read_b128 v[188:191], v204 offset:20480
	ds_read_b128 v[192:195], v204 offset:21504
	ds_read_b128 v[196:199], v204 offset:22528
	ds_read_b128 v[206:209], v204 offset:23552
	global_load_lds_dwordx4 v[210:211], off
	s_mov_b32 m0, s37
	s_addc_u32 vcc_hi, vcc_hi, 0
	global_load_lds_dwordx4 v[212:213], off
	v_lshl_add_u64 v[214:215], vcc, 0, v[112:113]
	s_mov_b32 m0, s57
	v_lshl_add_u64 v[216:217], vcc, 0, v[166:167]
	global_load_lds_dwordx4 v[214:215], off
	s_mov_b32 m0, s58
	v_lshl_add_u64 v[218:219], s[0:1], 0, v[162:163]
	global_load_lds_dwordx4 v[216:217], off
	s_mov_b32 m0, s59
	v_lshl_add_u64 v[220:221], s[0:1], 0, v[164:165]
	global_load_lds_dwordx4 v[218:219], off
	s_mov_b32 m0, s82
	s_nop 0
	global_load_lds_dwordx4 v[220:221], off
	s_waitcnt vmcnt(8)
	s_waitcnt lgkmcnt(0)
	s_barrier
	s_setprio 1
	s_waitcnt lgkmcnt(0)
	v_mfma_f32_16x16x32_bf16 v[28:31], v[130:133], v[172:175], v[28:31]
	v_mfma_f32_16x16x32_bf16 v[24:27], v[138:141], v[172:175], v[24:27]
	v_mfma_f32_16x16x32_bf16 v[20:23], v[130:133], v[180:183], v[20:23]
	v_mfma_f32_16x16x32_bf16 v[16:19], v[138:141], v[180:183], v[16:19]
	v_mfma_f32_16x16x32_bf16 v[12:15], v[130:133], v[188:191], v[12:15]
	v_mfma_f32_16x16x32_bf16 v[8:11], v[138:141], v[188:191], v[8:11]
	v_mfma_f32_16x16x32_bf16 v[4:7], v[130:133], v[196:199], v[4:7]
	v_mfma_f32_16x16x32_bf16 v[0:3], v[138:141], v[196:199], v[0:3]
	v_mfma_f32_16x16x32_bf16 v[28:31], v[134:137], v[176:179], v[28:31]
	v_mfma_f32_16x16x32_bf16 v[24:27], v[142:145], v[176:179], v[24:27]
	v_mfma_f32_16x16x32_bf16 v[20:23], v[134:137], v[184:187], v[20:23]
	v_mfma_f32_16x16x32_bf16 v[16:19], v[142:145], v[184:187], v[16:19]
	v_mfma_f32_16x16x32_bf16 v[12:15], v[134:137], v[192:195], v[12:15]
	v_mfma_f32_16x16x32_bf16 v[8:11], v[142:145], v[192:195], v[8:11]
	v_mfma_f32_16x16x32_bf16 v[4:7], v[134:137], v[206:209], v[4:7]
	v_mfma_f32_16x16x32_bf16 v[0:3], v[142:145], v[206:209], v[0:3]
	s_setprio 0
	s_setprio 1
	v_mfma_f32_16x16x32_bf16 v[92:95], v[146:149], v[172:175], v[92:95]
	v_mfma_f32_16x16x32_bf16 v[88:91], v[154:157], v[172:175], v[88:91]
	v_mfma_f32_16x16x32_bf16 v[84:87], v[146:149], v[180:183], v[84:87]
	v_mfma_f32_16x16x32_bf16 v[80:83], v[154:157], v[180:183], v[80:83]
	v_mfma_f32_16x16x32_bf16 v[76:79], v[146:149], v[188:191], v[76:79]
	v_mfma_f32_16x16x32_bf16 v[72:75], v[154:157], v[188:191], v[72:75]
	v_mfma_f32_16x16x32_bf16 v[64:67], v[146:149], v[196:199], v[64:67]
	v_mfma_f32_16x16x32_bf16 v[60:63], v[154:157], v[196:199], v[60:63]
	v_mfma_f32_16x16x32_bf16 v[92:95], v[150:153], v[176:179], v[92:95]
	v_mfma_f32_16x16x32_bf16 v[88:91], v[158:161], v[176:179], v[88:91]
	v_mfma_f32_16x16x32_bf16 v[84:87], v[150:153], v[184:187], v[84:87]
	v_mfma_f32_16x16x32_bf16 v[80:83], v[158:161], v[184:187], v[80:83]
	v_mfma_f32_16x16x32_bf16 v[76:79], v[150:153], v[192:195], v[76:79]
	v_mfma_f32_16x16x32_bf16 v[72:75], v[158:161], v[192:195], v[72:75]
	v_mfma_f32_16x16x32_bf16 v[64:67], v[150:153], v[206:209], v[64:67]
	v_mfma_f32_16x16x32_bf16 v[60:63], v[158:161], v[206:209], v[60:63]
	s_setprio 0
	s_barrier
	v_add_u32_e32 v142, s85, v201
	v_add_u32_e32 v158, s90, v201
	ds_read_b128 v[130:133], v142
	ds_read_b128 v[134:137], v142 offset:1024
	ds_read_b128 v[138:141], v142 offset:2048
	ds_read_b128 v[142:145], v142 offset:3072
	ds_read_b128 v[146:149], v158
	ds_read_b128 v[150:153], v158 offset:1024
	ds_read_b128 v[154:157], v158 offset:2048
	ds_read_b128 v[158:161], v158 offset:3072
	s_add_u32 s0, s0, s66
	s_addc_u32 s1, s1, 0
	s_mov_b32 m0, s83
	v_lshl_add_u64 v[222:223], s[0:1], 0, v[162:163]
	ds_read_b128 v[172:175], v204 offset:32768
	ds_read_b128 v[176:179], v204 offset:33792
	ds_read_b128 v[180:183], v204 offset:34816
	ds_read_b128 v[184:187], v204 offset:35840
	ds_read_b128 v[188:191], v204 offset:36864
	ds_read_b128 v[192:195], v204 offset:37888
	ds_read_b128 v[196:199], v204 offset:38912
	ds_read_b128 v[206:209], v204 offset:39936
	global_load_lds_dwordx4 v[222:223], off
	v_lshl_add_u64 v[222:223], s[0:1], 0, v[164:165]
	s_mov_b32 m0, s84
	s_nop 0
	global_load_lds_dwordx4 v[222:223], off
	s_waitcnt vmcnt(8)
	s_waitcnt lgkmcnt(0)
	s_barrier
	s_setprio 1
	s_waitcnt lgkmcnt(0)
	v_mfma_f32_16x16x32_bf16 v[68:71], v[130:133], v[172:175], v[68:71]
	v_mfma_f32_16x16x32_bf16 v[56:59], v[138:141], v[172:175], v[56:59]
	v_mfma_f32_16x16x32_bf16 v[52:55], v[130:133], v[180:183], v[52:55]
	v_mfma_f32_16x16x32_bf16 v[48:51], v[138:141], v[180:183], v[48:51]
	v_mfma_f32_16x16x32_bf16 v[44:47], v[130:133], v[188:191], v[44:47]
	v_mfma_f32_16x16x32_bf16 v[40:43], v[138:141], v[188:191], v[40:43]
	v_mfma_f32_16x16x32_bf16 v[36:39], v[130:133], v[196:199], v[36:39]
	v_mfma_f32_16x16x32_bf16 v[32:35], v[138:141], v[196:199], v[32:35]
	v_mfma_f32_16x16x32_bf16 v[68:71], v[134:137], v[176:179], v[68:71]
	v_mfma_f32_16x16x32_bf16 v[56:59], v[142:145], v[176:179], v[56:59]
	v_mfma_f32_16x16x32_bf16 v[52:55], v[134:137], v[184:187], v[52:55]
	v_mfma_f32_16x16x32_bf16 v[48:51], v[142:145], v[184:187], v[48:51]
	v_mfma_f32_16x16x32_bf16 v[44:47], v[134:137], v[192:195], v[44:47]
	v_mfma_f32_16x16x32_bf16 v[40:43], v[142:145], v[192:195], v[40:43]
	v_mfma_f32_16x16x32_bf16 v[36:39], v[134:137], v[206:209], v[36:39]
	v_mfma_f32_16x16x32_bf16 v[32:35], v[142:145], v[206:209], v[32:35]
	s_setprio 0
	s_setprio 1
	v_mfma_f32_16x16x32_bf16 v[126:129], v[146:149], v[172:175], v[126:129]
	v_mfma_f32_16x16x32_bf16 v[122:125], v[154:157], v[172:175], v[122:125]
	v_mfma_f32_16x16x32_bf16 v[118:121], v[146:149], v[180:183], v[118:121]
	v_mfma_f32_16x16x32_bf16 v[114:117], v[154:157], v[180:183], v[114:117]
	v_mfma_f32_16x16x32_bf16 v[108:111], v[146:149], v[188:191], v[108:111]
	v_mfma_f32_16x16x32_bf16 v[104:107], v[154:157], v[188:191], v[104:107]
	v_mfma_f32_16x16x32_bf16 v[100:103], v[146:149], v[196:199], v[100:103]
	v_mfma_f32_16x16x32_bf16 v[96:99], v[154:157], v[196:199], v[96:99]
	v_mfma_f32_16x16x32_bf16 v[126:129], v[150:153], v[176:179], v[126:129]
	v_mfma_f32_16x16x32_bf16 v[122:125], v[158:161], v[176:179], v[122:125]
	v_mfma_f32_16x16x32_bf16 v[118:121], v[150:153], v[184:187], v[118:121]
	v_mfma_f32_16x16x32_bf16 v[114:117], v[158:161], v[184:187], v[114:117]
	v_mfma_f32_16x16x32_bf16 v[108:111], v[150:153], v[192:195], v[108:111]
	v_mfma_f32_16x16x32_bf16 v[104:107], v[158:161], v[192:195], v[104:107]
	v_mfma_f32_16x16x32_bf16 v[100:103], v[150:153], v[206:209], v[100:103]
	v_mfma_f32_16x16x32_bf16 v[96:99], v[158:161], v[206:209], v[96:99]
	s_setprio 0
	s_barrier
	s_mov_b32 m0, s86
	v_lshl_add_u64 v[210:211], v[210:211], 0, s[16:17]
	ds_read_b128 v[172:175], v204 offset:49152
	ds_read_b128 v[176:179], v204 offset:50176
	ds_read_b128 v[180:183], v204 offset:51200
	ds_read_b128 v[184:187], v204 offset:52224
	ds_read_b128 v[188:191], v204 offset:53248
	ds_read_b128 v[192:195], v204 offset:54272
	ds_read_b128 v[196:199], v204 offset:55296
	ds_read_b128 v[206:209], v204 offset:56320
	global_load_lds_dwordx4 v[210:211], off
	v_lshl_add_u64 v[210:211], v[212:213], 0, s[16:17]
	s_mov_b32 m0, s87
	s_nop 0
	global_load_lds_dwordx4 v[210:211], off
	v_lshl_add_u64 v[210:211], v[214:215], 0, s[16:17]
	s_mov_b32 m0, s91
	s_nop 0
	global_load_lds_dwordx4 v[210:211], off
	v_lshl_add_u64 v[210:211], v[216:217], 0, s[16:17]
	s_mov_b32 m0, s92
	s_nop 0
	global_load_lds_dwordx4 v[210:211], off
	v_lshl_add_u64 v[210:211], v[218:219], 0, s[16:17]
	s_mov_b32 m0, s88
	s_nop 0
	global_load_lds_dwordx4 v[210:211], off
	v_lshl_add_u64 v[210:211], v[220:221], 0, s[16:17]
	s_mov_b32 m0, s89
	s_nop 0
	global_load_lds_dwordx4 v[210:211], off
	s_waitcnt vmcnt(8)
	s_waitcnt lgkmcnt(0)
	s_barrier
	s_setprio 1
	s_waitcnt lgkmcnt(0)
	v_mfma_f32_16x16x32_bf16 v[28:31], v[130:133], v[172:175], v[28:31]
	v_mfma_f32_16x16x32_bf16 v[24:27], v[138:141], v[172:175], v[24:27]
	v_mfma_f32_16x16x32_bf16 v[20:23], v[130:133], v[180:183], v[20:23]
	v_mfma_f32_16x16x32_bf16 v[16:19], v[138:141], v[180:183], v[16:19]
	v_mfma_f32_16x16x32_bf16 v[12:15], v[130:133], v[188:191], v[12:15]
	v_mfma_f32_16x16x32_bf16 v[8:11], v[138:141], v[188:191], v[8:11]
	v_mfma_f32_16x16x32_bf16 v[4:7], v[130:133], v[196:199], v[4:7]
	v_mfma_f32_16x16x32_bf16 v[0:3], v[138:141], v[196:199], v[0:3]
	v_mfma_f32_16x16x32_bf16 v[28:31], v[134:137], v[176:179], v[28:31]
	v_mfma_f32_16x16x32_bf16 v[24:27], v[142:145], v[176:179], v[24:27]
	v_mfma_f32_16x16x32_bf16 v[20:23], v[134:137], v[184:187], v[20:23]
	v_mfma_f32_16x16x32_bf16 v[16:19], v[142:145], v[184:187], v[16:19]
	v_mfma_f32_16x16x32_bf16 v[12:15], v[134:137], v[192:195], v[12:15]
	v_mfma_f32_16x16x32_bf16 v[8:11], v[142:145], v[192:195], v[8:11]
	v_mfma_f32_16x16x32_bf16 v[4:7], v[134:137], v[206:209], v[4:7]
	v_mfma_f32_16x16x32_bf16 v[0:3], v[142:145], v[206:209], v[0:3]
	s_setprio 0
	s_setprio 1
	v_mfma_f32_16x16x32_bf16 v[92:95], v[146:149], v[172:175], v[92:95]
	v_mfma_f32_16x16x32_bf16 v[88:91], v[154:157], v[172:175], v[88:91]
	v_mfma_f32_16x16x32_bf16 v[84:87], v[146:149], v[180:183], v[84:87]
	v_mfma_f32_16x16x32_bf16 v[80:83], v[154:157], v[180:183], v[80:83]
	v_mfma_f32_16x16x32_bf16 v[76:79], v[146:149], v[188:191], v[76:79]
	v_mfma_f32_16x16x32_bf16 v[72:75], v[154:157], v[188:191], v[72:75]
	v_mfma_f32_16x16x32_bf16 v[64:67], v[146:149], v[196:199], v[64:67]
	v_mfma_f32_16x16x32_bf16 v[60:63], v[154:157], v[196:199], v[60:63]
	v_mfma_f32_16x16x32_bf16 v[92:95], v[150:153], v[176:179], v[92:95]
	v_mfma_f32_16x16x32_bf16 v[88:91], v[158:161], v[176:179], v[88:91]
	v_mfma_f32_16x16x32_bf16 v[84:87], v[150:153], v[184:187], v[84:87]
	v_mfma_f32_16x16x32_bf16 v[80:83], v[158:161], v[184:187], v[80:83]
	v_mfma_f32_16x16x32_bf16 v[76:79], v[150:153], v[192:195], v[76:79]
	v_mfma_f32_16x16x32_bf16 v[72:75], v[158:161], v[192:195], v[72:75]
	v_mfma_f32_16x16x32_bf16 v[64:67], v[150:153], v[206:209], v[64:67]
	v_mfma_f32_16x16x32_bf16 v[60:63], v[158:161], v[206:209], v[60:63]
	s_setprio 0
	s_barrier
	s_add_u32 s80, s80, 0x100
	s_addc_u32 s81, s81, 0
	s_add_u32 s4, s4, 0x100
	s_addc_u32 s5, s5, 0
	s_cmp_ge_u32 s6, s93
	s_mov_b32 s0, s6
	s_cbranch_scc0 .LBB0_598
	s_and_b64 vcc, exec, s[20:21]
	s_cbranch_vccz .LBB0_601
	s_barrier
